# final_norm: per-segment g_final loads hoisted ahead of the row-sum reduction so no vmcnt(0) waits on the nontemporal stores inside a trip
# speedup vs baseline: 1.0070x; 1.0070x over previous
.LBB0_2643:
	v_ashrrev_i32_e32 v33, 31, v32
	v_lshlrev_b64 v[46:47], 12, v[32:33]
	v_add_u32_e32 v59, s8, v32
	v_lshl_add_u64 v[44:45], v[38:39], 0, v[46:47]
	v_cmp_gt_i32_e32 vcc, s7, v59
	global_load_dwordx4 v[60:63], v[44:45], off nt
	global_load_dwordx4 v[16:19], v[44:45], off offset:1024 nt
	global_load_dwordx4 v[0:3], v[44:45], off offset:3072 nt
	global_load_dwordx4 v[12:15], v[44:45], off offset:2048 nt
	v_cndmask_b32_e32 v34, v32, v59, vcc
	v_ashrrev_i32_e32 v35, 31, v34
	v_lshlrev_b64 v[42:43], 12, v[34:35]
	v_lshl_add_u64 v[48:49], v[38:39], 0, v[42:43]
	global_load_dwordx4 v[24:27], v[48:49], off nt
	global_load_dwordx4 v[20:23], v[48:49], off offset:1024 nt
	global_load_dwordx4 v[4:7], v[48:49], off offset:3072 nt
	global_load_dwordx4 v[8:11], v[48:49], off offset:2048 nt
	global_load_dwordx4 v[28:31], v[36:37], off
	v_cmp_ne_u32_e32 vcc, v32, v34
	s_waitcnt vmcnt(0)
	v_pk_mul_f32 v[50:51], v[62:63], v[62:63]
	v_pk_mul_f32 v[52:53], v[60:61], v[60:61]
	v_pk_mul_f32 v[64:65], v[18:19], v[18:19]
	v_pk_mul_f32 v[66:67], v[16:17], v[16:17]
	v_mul_f32_e32 v68, v13, v13
	v_mul_f32_e32 v70, v15, v15
	v_pk_mov_b32 v[72:73], v[52:53], v[50:51] op_sel:[1,0]
	v_mov_b32_e32 v53, v51
	v_pk_mov_b32 v[50:51], v[66:67], v[64:65] op_sel:[1,0]
	v_mov_b32_e32 v67, v65
	v_pk_fma_f32 v[64:65], v[12:13], v[12:13], v[68:69] op_sel_hi:[1,1,0]
	v_pk_fma_f32 v[68:69], v[14:15], v[14:15], v[70:71] op_sel_hi:[1,1,0]
	v_pk_add_f32 v[52:53], v[72:73], v[52:53]
	v_pk_mul_f32 v[70:71], v[26:27], v[26:27]
	v_pk_mul_f32 v[72:73], v[24:25], v[24:25]
	v_pk_add_f32 v[50:51], v[50:51], v[66:67]
	v_pk_mul_f32 v[66:67], v[22:23], v[22:23]
	v_pk_mul_f32 v[74:75], v[20:21], v[20:21]
	v_mul_f32_e32 v33, v0, v0
	v_mul_f32_e32 v35, v1, v1
	v_mul_f32_e32 v76, v2, v2
	v_mul_f32_e32 v77, v3, v3
	v_pk_mov_b32 v[80:81], v[72:73], v[70:71] op_sel:[1,0]
	v_mov_b32_e32 v73, v71
	v_pk_mov_b32 v[70:71], v[74:75], v[66:67] op_sel:[1,0]
	v_mov_b32_e32 v75, v67
	v_pk_add_f32 v[52:53], v[52:53], v[52:53] op_sel:[0,1] op_sel_hi:[1,0]
	v_pk_add_f32 v[50:51], v[50:51], v[50:51] op_sel:[0,1] op_sel_hi:[1,0]
	v_mov_b32_e32 v65, v76
	v_mov_b32_e32 v69, v77
	v_mul_f32_e32 v77, v4, v4
	v_mul_f32_e32 v79, v5, v5
	v_mul_f32_e32 v76, v9, v9
	v_mul_f32_e32 v78, v11, v11
	v_pk_add_f32 v[72:73], v[80:81], v[72:73]
	v_pk_add_f32 v[70:71], v[70:71], v[74:75]
	v_mov_b32_e32 v53, v33
	v_mov_b32_e32 v51, v35
	v_mul_f32_e32 v82, v6, v6
	v_mul_f32_e32 v83, v7, v7
	v_pk_add_f32 v[64:65], v[64:65], v[68:69]
	v_pk_fma_f32 v[66:67], v[8:9], v[8:9], v[76:77] op_sel_hi:[1,1,0]
	v_pk_fma_f32 v[68:69], v[10:11], v[10:11], v[78:79] op_sel_hi:[1,1,0]
	v_pk_add_f32 v[50:51], v[52:53], v[50:51]
	v_pk_add_f32 v[52:53], v[72:73], v[72:73] op_sel:[0,1] op_sel_hi:[1,0]
	v_pk_add_f32 v[70:71], v[70:71], v[70:71] op_sel:[0,1] op_sel_hi:[1,0]
	v_mov_b32_e32 v67, v82
	v_mov_b32_e32 v69, v83
	v_mov_b32_e32 v53, v77
	v_mov_b32_e32 v71, v79
	v_pk_add_f32 v[66:67], v[66:67], v[68:69]
	v_pk_add_f32 v[52:53], v[52:53], v[70:71]
	v_pk_add_f32 v[50:51], v[50:51], v[64:65]
	v_pk_add_f32 v[52:53], v[52:53], v[66:67]
	v_mov_b32_e32 v65, v50
	v_mov_b32_e32 v64, v52
	v_mov_b32_e32 v50, v53
	v_pk_add_f32 v[50:51], v[64:65], v[50:51]
	global_load_dwordx4 v[84:87], v[36:37], off offset:1024
	global_load_dwordx4 v[88:91], v[36:37], off offset:1024
	global_load_dwordx4 v[92:95], v[36:37], off offset:2048
	global_load_dwordx4 v[96:99], v[36:37], off offset:3072
	global_load_dwordx4 v[100:103], v[36:37], off offset:3072
	ds_bpermute_b32 v53, v41, v51
	ds_bpermute_b32 v52, v41, v50
	s_waitcnt lgkmcnt(0)
	v_pk_add_f32 v[50:51], v[50:51], v[52:53]
	ds_bpermute_b32 v53, v54, v51
	ds_bpermute_b32 v52, v54, v50
	s_waitcnt lgkmcnt(0)
	v_pk_add_f32 v[50:51], v[50:51], v[52:53]
	ds_bpermute_b32 v53, v55, v51
	ds_bpermute_b32 v52, v55, v50
	s_waitcnt lgkmcnt(0)
	v_pk_add_f32 v[50:51], v[50:51], v[52:53]
	ds_bpermute_b32 v53, v56, v51
	ds_bpermute_b32 v52, v56, v50
	s_waitcnt lgkmcnt(0)
	v_pk_add_f32 v[50:51], v[50:51], v[52:53]
	ds_bpermute_b32 v53, v57, v51
	ds_bpermute_b32 v52, v57, v50
	s_waitcnt lgkmcnt(0)
	v_pk_add_f32 v[50:51], v[50:51], v[52:53]
	ds_bpermute_b32 v53, v58, v51
	ds_bpermute_b32 v52, v58, v50
	s_waitcnt lgkmcnt(0)
	s_waitcnt vmcnt(0)
	v_pk_add_f32 v[50:51], v[50:51], v[52:53]
	s_nop 0
	v_pk_fma_f32 v[50:51], v[50:51], s[6:7], v[40:41] op_sel_hi:[1,0,0]
	s_nop 0
	v_mul_f32_e32 v33, 0x4b800000, v51
	v_cmp_gt_f32_e64 s[0:1], s9, v51
	v_mul_f32_e32 v35, 0x4b800000, v50
	v_cmp_gt_f32_e64 s[2:3], s9, v50
	v_cndmask_b32_e64 v33, v51, v33, s[0:1]
	v_rsq_f32_e32 v33, v33
	v_cndmask_b32_e64 v35, v50, v35, s[2:3]
	v_rsq_f32_e32 v35, v35
	v_mul_f32_e32 v32, 0x45800000, v33
	v_cndmask_b32_e64 v52, v33, v32, s[0:1]
	v_mul_f32_e32 v34, 0x45800000, v35
	v_mov_b32_e32 v53, v52
	v_cndmask_b32_e64 v50, v35, v34, s[2:3]
	v_pk_mul_f32 v[32:33], v[60:61], v[52:53] op_sel_hi:[1,0]
	v_pk_mul_f32 v[34:35], v[62:63], v[52:53] op_sel_hi:[1,0]
	v_mov_b32_e32 v51, v50
	v_pk_mul_f32 v[34:35], v[30:31], v[34:35]
	v_pk_mul_f32 v[32:33], v[28:29], v[32:33]
	v_pk_mul_f32 v[16:17], v[16:17], v[52:53]
	global_store_dwordx4 v[44:45], v[32:35], off nt
	s_and_saveexec_b64 s[0:1], vcc
	s_xor_b64 s[0:1], exec, s[0:1]
	s_cbranch_execz .LBB0_2645
	v_mov_b32_e32 v32, v50
	v_mov_b32_e32 v33, v50
	v_pk_mul_f32 v[26:27], v[26:27], v[32:33]
	v_pk_mul_f32 v[24:25], v[24:25], v[50:51]
	v_pk_mul_f32 v[26:27], v[30:31], v[26:27]
	v_pk_mul_f32 v[24:25], v[28:29], v[24:25]
	global_store_dwordx4 v[48:49], v[24:27], off nt
	s_nop 1
	v_mov_b64_e32 v[24:25], v[84:85]
	v_mov_b64_e32 v[26:27], v[86:87]
	v_mov_b32_e32 v28, v52
	v_mov_b32_e32 v29, v52
	v_pk_mul_f32 v[18:19], v[18:19], v[28:29]
	v_pk_mul_f32 v[20:21], v[20:21], v[50:51]
	v_pk_mul_f32 v[22:23], v[22:23], v[32:33]
	s_nop 0
	v_pk_mul_f32 v[18:19], v[18:19], v[26:27]
	v_pk_mul_f32 v[16:17], v[16:17], v[24:25]
	v_pk_mul_f32 v[34:35], v[22:23], v[26:27]
	global_store_dwordx4 v[44:45], v[16:19], off offset:1024 nt
	v_pk_mul_f32 v[32:33], v[20:21], v[24:25]
.LBB0_2645:
	s_or_saveexec_b64 s[0:1], s[0:1]
	v_mov_b64_e32 v[20:21], v[42:43]
	s_xor_b64 exec, exec, s[0:1]
	s_cbranch_execz .LBB0_2647
	v_mov_b64_e32 v[20:21], v[88:89]
	v_mov_b64_e32 v[22:23], v[90:91]
	v_mov_b32_e32 v24, v52
	v_mov_b32_e32 v25, v52
	v_pk_mul_f32 v[18:19], v[18:19], v[24:25]
	s_nop 0
	v_pk_mul_f32 v[32:33], v[16:17], v[20:21]
	v_pk_mul_f32 v[34:35], v[18:19], v[22:23]
	v_mov_b64_e32 v[20:21], v[46:47]
.LBB0_2647:
	s_or_b64 exec, exec, s[0:1]
	v_lshl_add_u64 v[16:17], v[38:39], 0, v[20:21]
	global_store_dwordx4 v[16:17], v[32:35], off offset:1024 nt
	v_mov_b64_e32 v[16:17], v[92:93]
	v_mov_b64_e32 v[18:19], v[94:95]
	v_mov_b32_e32 v20, v52
	v_mov_b32_e32 v21, v52
	v_pk_mul_f32 v[12:13], v[12:13], v[52:53]
	v_pk_mul_f32 v[14:15], v[14:15], v[20:21]
	v_pk_mul_f32 v[0:1], v[0:1], v[52:53]
	s_nop 0
	v_pk_mul_f32 v[14:15], v[14:15], v[18:19]
	v_pk_mul_f32 v[12:13], v[12:13], v[16:17]
	global_store_dwordx4 v[44:45], v[12:15], off offset:2048 nt
	s_and_saveexec_b64 s[0:1], vcc
	s_xor_b64 s[0:1], exec, s[0:1]
	s_cbranch_execz .LBB0_2649
	v_mov_b32_e32 v12, v50
	v_mov_b32_e32 v13, v50
	v_pk_mul_f32 v[10:11], v[10:11], v[12:13]
	v_pk_mul_f32 v[8:9], v[8:9], v[50:51]
	v_pk_mul_f32 v[10:11], v[10:11], v[18:19]
	v_pk_mul_f32 v[8:9], v[8:9], v[16:17]
	global_store_dwordx4 v[48:49], v[8:11], off offset:2048 nt
	s_nop 1
	v_mov_b64_e32 v[8:9], v[96:97]
	v_mov_b64_e32 v[10:11], v[98:99]
	v_pk_mul_f32 v[2:3], v[2:3], v[20:21]
	v_pk_mul_f32 v[4:5], v[4:5], v[50:51]
	v_pk_mul_f32 v[6:7], v[6:7], v[12:13]
	s_nop 0
	v_pk_mul_f32 v[2:3], v[2:3], v[10:11]
	v_pk_mul_f32 v[0:1], v[0:1], v[8:9]
	v_pk_mul_f32 v[14:15], v[6:7], v[10:11]
	global_store_dwordx4 v[44:45], v[0:3], off offset:3072 nt
	v_pk_mul_f32 v[12:13], v[4:5], v[8:9]
.LBB0_2649:
	s_andn2_saveexec_b64 s[0:1], s[0:1]
	s_cbranch_execz .LBB0_2642
	v_mov_b64_e32 v[4:5], v[100:101]
	v_mov_b64_e32 v[6:7], v[102:103]
	v_mov_b32_e32 v53, v52
	v_pk_mul_f32 v[2:3], v[2:3], v[52:53]
	v_mov_b64_e32 v[42:43], v[46:47]
	s_nop 0
	v_pk_mul_f32 v[14:15], v[2:3], v[6:7]
	v_pk_mul_f32 v[12:13], v[0:1], v[4:5]
	s_branch .LBB0_2642
